# scan consumer waves at raised priority during the chunk; y-path reordered to drop the last hazard nop
# baseline (speedup 1.0000x reference)
; DI void scan_item(const __attribute__((address_space(4))) Args& a, LAS unsigned char* lds, int ws_, bool is_prompt, int seq, int h, int half, bool dry = false) {
;     ...
;     auto consume = [&](int bsel) {
;         const LAS unsigned char* B = lds + bsel * SC_BUF;
;         const LAS float* opb = (const LAS float*)B + c0;
;         const LAS float* vvb = (const LAS float*)(B + SC_OPS) + i0;
;         const LAS float* scb = (const LAS float*)(B + SC_OPS + SC_VV);
;         LAS float* ybb = cg8 == 0 ? (LAS float*)(B + SC_OPS + SC_VV + SC_SC) + (i0 & 31) : (LAS float*)(lds + 2 * SC_BUF) + (tid & 255);
;         f32x4 n[10]; float nv; f32x2 nbk;
;     ...
;         SC_LOAD(0)
; #pragma unroll 4
;         for (int t = 0; t < SC_CH; ++t) {
;             f32x4 c[10];
; #pragma unroll
;             for (int q = 0; q < 10; ++q) c[q] = n[q];
;             const float v0 = nv; const f32x2 bk = nbk;
;             SC_LOAD(t + 1)
;             __builtin_amdgcn_sched_barrier(0);
;             f32x2 aA = sp[0] * c[0].xy, aY = sp[0] * c[2].xy;
;             aA = sp[1] * c[0].zw + aA; aY = sp[1] * c[2].zw + aY;
;             aA = sp[2] * c[1].xy + aA; aY = sp[2] * c[3].xy + aY;
;             aA = sp[3] * c[1].zw + aA; aY = sp[3] * c[3].zw + aY;
;             float da = aA.x + aA.y, dy = aY.x + aY.y;
;             asm("s_nop 1\n\t"
;                 "v_add_f32_dpp %0, %0, %0 quad_perm:[1,0,3,2] row_mask:0xf bank_mask:0xf bound_ctrl:1\n\t"
;                 "v_add_f32_dpp %1, %1, %1 quad_perm:[1,0,3,2] row_mask:0xf bank_mask:0xf bound_ctrl:1\n\t"
;                 "s_nop 0\n\t"
;                 "v_add_f32_dpp %0, %0, %0 quad_perm:[2,3,0,1] row_mask:0xf bank_mask:0xf bound_ctrl:1\n\t"
;                 "v_add_f32_dpp %1, %1, %1 quad_perm:[2,3,0,1] row_mask:0xf bank_mask:0xf bound_ctrl:1\n\t"
;                 "s_nop 0\n\t"
;                 "v_add_f32_dpp %0, %0, %0 row_half_mirror row_mask:0xf bank_mask:0xf bound_ctrl:1\n\t"
;                 "v_add_f32_dpp %1, %1, %1 row_half_mirror row_mask:0xf bank_mask:0xf bound_ctrl:1"
;                 : "+v"(da), "+v"(dy));
;             {
;                 f32x2 t0;
;                 t0 = c[8].xy * v0; t0 = c[6].xy * da + t0; sp[0] = sp[0] * c[4].xy + t0;
;                 t0 = c[8].zw * v0; t0 = c[6].zw * da + t0; sp[1] = sp[1] * c[4].zw + t0;
;                 t0 = c[9].xy * v0; t0 = c[7].xy * da + t0; sp[2] = sp[2] * c[5].xy + t0;
.LBB0_1535:
	s_and_b64 vcc, exec, s[74:75]
	s_cbranch_vccz .LBB0_1523
	s_setprio 3
	s_bitcmp1_b32 s24, 0
	s_cselect_b32 s34, 0x6900, 0
	s_add_i32 s35, s34, 0
	s_waitcnt vmcnt(0)
	v_lshl_add_u32 v120, v110, 2, s35
	v_lshl_add_u32 v96, v111, 2, s35
	v_lshl_add_u32 v136, v115, 2, s35
	v_mov_b32_e32 v121, s35
	v_add_u32_e32 v136, 0x6100, v136
	v_cndmask_b32_e64 v95, v116, v136, s[8:9]
	ds_read_b128 v[40:43], v120
	ds_read_b128 v[44:47], v120 offset:16
	ds_read_b128 v[48:51], v120 offset:256
	ds_read_b128 v[52:55], v120 offset:272
	ds_read_b128 v[56:59], v120 offset:512
	ds_read_b128 v[60:63], v120 offset:528
	ds_read_b128 v[64:67], v120 offset:768
	ds_read_b128 v[68:71], v120 offset:784
	ds_read_b128 v[72:75], v120 offset:1024
	ds_read_b128 v[76:79], v120 offset:1040
	ds_read_b32 v94, v96 offset:20480
	ds_read_b64 v[108:109], v121 offset:24576
	ds_read_b128 v[190:193], v120 offset:1280
	ds_read_b128 v[194:197], v120 offset:1296
	ds_read_b128 v[198:201], v120 offset:1536
	ds_read_b128 v[202:205], v120 offset:1552
	ds_read_b128 v[206:209], v120 offset:1792
	ds_read_b128 v[210:213], v120 offset:1808
	ds_read_b128 v[214:217], v120 offset:2048
	ds_read_b128 v[218:221], v120 offset:2064
	ds_read_b128 v[222:225], v120 offset:2304
	ds_read_b128 v[226:229], v120 offset:2320
	ds_read_b32 v230, v96 offset:20736
	ds_read_b64 v[232:233], v121 offset:24592
	s_waitcnt lgkmcnt(12)
	v_pk_mul_f32 v[122:123], v[38:39], v[42:43]
	v_pk_mul_f32 v[124:125], v[38:39], v[50:51]
	v_pk_fma_f32 v[122:123], v[36:37], v[40:41], v[122:123]
	v_pk_fma_f32 v[124:125], v[36:37], v[48:49], v[124:125]
	v_pk_fma_f32 v[122:123], v[32:33], v[44:45], v[122:123]
	v_pk_fma_f32 v[124:125], v[32:33], v[52:53], v[124:125]
	v_pk_fma_f32 v[122:123], v[34:35], v[46:47], v[122:123]
	v_pk_fma_f32 v[124:125], v[34:35], v[54:55], v[124:125]
	v_pk_mul_f32 v[126:127], v[72:73], v[94:95] op_sel_hi:[1,0]
	v_add_f32_e32 v166, v122, v123
	v_add_f32_e32 v168, v124, v125
	v_pk_mul_f32 v[128:129], v[74:75], v[94:95] op_sel_hi:[1,0]
	v_pk_mul_f32 v[130:131], v[76:77], v[94:95] op_sel_hi:[1,0]
	v_add_f32_dpp v166, v166, v166 quad_perm:[1,0,3,2] row_mask:0xf bank_mask:0xf bound_ctrl:1
	v_add_f32_dpp v168, v168, v168 quad_perm:[1,0,3,2] row_mask:0xf bank_mask:0xf bound_ctrl:1
	v_pk_mul_f32 v[132:133], v[78:79], v[94:95] op_sel_hi:[1,0]
	v_pk_fma_f32 v[126:127], v[36:37], v[56:57], v[126:127]
	v_add_f32_dpp v166, v166, v166 quad_perm:[2,3,0,1] row_mask:0xf bank_mask:0xf bound_ctrl:1
	v_add_f32_dpp v168, v168, v168 quad_perm:[2,3,0,1] row_mask:0xf bank_mask:0xf bound_ctrl:1
	v_pk_fma_f32 v[128:129], v[38:39], v[58:59], v[128:129]
	v_pk_fma_f32 v[130:131], v[32:33], v[60:61], v[130:131]
	v_add_f32_dpp v166, v166, v166 row_half_mirror row_mask:0xf bank_mask:0xf bound_ctrl:1
	v_add_f32_dpp v168, v168, v168 row_half_mirror row_mask:0xf bank_mask:0xf bound_ctrl:1
	v_pk_fma_f32 v[132:133], v[34:35], v[62:63], v[132:133]
	v_mov_b32_e32 v167, v94
	v_pk_mul_f32 v[134:135], v[166:167], v[108:109]
	v_pk_fma_f32 v[36:37], v[64:65], v[166:167], v[126:127] op_sel_hi:[1,0,1]
	v_pk_fma_f32 v[38:39], v[66:67], v[166:167], v[128:129] op_sel_hi:[1,0,1]
	v_pk_fma_f32 v[32:33], v[68:69], v[166:167], v[130:131] op_sel_hi:[1,0,1]
	v_pk_fma_f32 v[34:35], v[70:71], v[166:167], v[132:133] op_sel_hi:[1,0,1]
	v_add_f32_e32 v136, v168, v134
	v_add_f32_e32 v136, v135, v136
	ds_write_b32 v95, v136
	ds_read_b128 v[40:43], v120 offset:2560
	ds_read_b128 v[44:47], v120 offset:2576
	ds_read_b128 v[48:51], v120 offset:2816
	ds_read_b128 v[52:55], v120 offset:2832
	ds_read_b128 v[56:59], v120 offset:3072
	ds_read_b128 v[60:63], v120 offset:3088
	ds_read_b128 v[64:67], v120 offset:3328
	ds_read_b128 v[68:71], v120 offset:3344
	ds_read_b128 v[72:75], v120 offset:3584
	ds_read_b128 v[76:79], v120 offset:3600
	ds_read_b32 v94, v96 offset:20992
	ds_read_b64 v[108:109], v121 offset:24608
	s_waitcnt lgkmcnt(12)
	v_pk_mul_f32 v[122:123], v[38:39], v[192:193]
	v_pk_mul_f32 v[124:125], v[38:39], v[200:201]
	v_pk_fma_f32 v[122:123], v[36:37], v[190:191], v[122:123]
	v_pk_fma_f32 v[124:125], v[36:37], v[198:199], v[124:125]
	v_pk_fma_f32 v[122:123], v[32:33], v[194:195], v[122:123]
	v_pk_fma_f32 v[124:125], v[32:33], v[202:203], v[124:125]
	v_pk_fma_f32 v[122:123], v[34:35], v[196:197], v[122:123]
	v_pk_fma_f32 v[124:125], v[34:35], v[204:205], v[124:125]
	v_pk_mul_f32 v[126:127], v[222:223], v[230:231] op_sel_hi:[1,0]
	v_add_f32_e32 v166, v122, v123
	v_add_f32_e32 v168, v124, v125
	v_pk_mul_f32 v[128:129], v[224:225], v[230:231] op_sel_hi:[1,0]
	v_pk_mul_f32 v[130:131], v[226:227], v[230:231] op_sel_hi:[1,0]
	v_add_f32_dpp v166, v166, v166 quad_perm:[1,0,3,2] row_mask:0xf bank_mask:0xf bound_ctrl:1
	v_add_f32_dpp v168, v168, v168 quad_perm:[1,0,3,2] row_mask:0xf bank_mask:0xf bound_ctrl:1
	v_pk_mul_f32 v[132:133], v[228:229], v[230:231] op_sel_hi:[1,0]
	v_pk_fma_f32 v[126:127], v[36:37], v[206:207], v[126:127]
	v_add_f32_dpp v166, v166, v166 quad_perm:[2,3,0,1] row_mask:0xf bank_mask:0xf bound_ctrl:1
	v_add_f32_dpp v168, v168, v168 quad_perm:[2,3,0,1] row_mask:0xf bank_mask:0xf bound_ctrl:1
	v_pk_fma_f32 v[128:129], v[38:39], v[208:209], v[128:129]
	v_pk_fma_f32 v[130:131], v[32:33], v[210:211], v[130:131]
	v_add_f32_dpp v166, v166, v166 row_half_mirror row_mask:0xf bank_mask:0xf bound_ctrl:1
	v_add_f32_dpp v168, v168, v168 row_half_mirror row_mask:0xf bank_mask:0xf bound_ctrl:1
	v_pk_fma_f32 v[132:133], v[34:35], v[212:213], v[132:133]
	v_mov_b32_e32 v167, v230
	v_pk_mul_f32 v[134:135], v[166:167], v[232:233]
	v_pk_fma_f32 v[36:37], v[214:215], v[166:167], v[126:127] op_sel_hi:[1,0,1]
	v_pk_fma_f32 v[38:39], v[216:217], v[166:167], v[128:129] op_sel_hi:[1,0,1]
	v_pk_fma_f32 v[32:33], v[218:219], v[166:167], v[130:131] op_sel_hi:[1,0,1]
	v_pk_fma_f32 v[34:35], v[220:221], v[166:167], v[132:133] op_sel_hi:[1,0,1]
	v_add_f32_e32 v136, v168, v134
	v_add_f32_e32 v136, v135, v136
	ds_write_b32 v95, v136 offset:128
	ds_read_b128 v[190:193], v120 offset:3840
	ds_read_b128 v[194:197], v120 offset:3856
	ds_read_b128 v[198:201], v120 offset:4096
	ds_read_b128 v[202:205], v120 offset:4112
	ds_read_b128 v[206:209], v120 offset:4352
	ds_read_b128 v[210:213], v120 offset:4368
	ds_read_b128 v[214:217], v120 offset:4608
	ds_read_b128 v[218:221], v120 offset:4624
	ds_read_b128 v[222:225], v120 offset:4864
	ds_read_b128 v[226:229], v120 offset:4880
	ds_read_b32 v230, v96 offset:21248
	ds_read_b64 v[232:233], v121 offset:24624
	s_waitcnt lgkmcnt(12)
; #define SC_LOAD(t) { _Pragma("unroll") for (int q = 0; q < 5; ++q) { n[2 * q] = *(const LAS f32x4*)(opb + (t) * 320 + q * 64); n[2 * q + 1] = *(const LAS f32x4*)(opb + (t) * 320 + q * 64 + 4); } \
;                      nv = vvb[(t) * 64]; nbk = *(const LAS f32x2*)(scb + (t) * 4); }
; DI void scan_item(const __attribute__((address_space(4))) Args& a, LAS unsigned char* lds, int ws_, bool is_prompt, int seq, int h, int half, bool dry = false) {
;     ...
; #pragma unroll 4
;         for (int t = 0; t < SC_CH; ++t) {
;             f32x4 c[10];
; #pragma unroll
;             for (int q = 0; q < 10; ++q) c[q] = n[q];
;             const float v0 = nv; const f32x2 bk = nbk;
;             SC_LOAD(t + 1)
;             __builtin_amdgcn_sched_barrier(0);
;             f32x2 aA = sp[0] * c[0].xy, aY = sp[0] * c[2].xy;
;             aA = sp[1] * c[0].zw + aA; aY = sp[1] * c[2].zw + aY;
;             aA = sp[2] * c[1].xy + aA; aY = sp[2] * c[3].xy + aY;
;             aA = sp[3] * c[1].zw + aA; aY = sp[3] * c[3].zw + aY;
;             float da = aA.x + aA.y, dy = aY.x + aY.y;
;             asm("s_nop 1\n\t"
;                 "v_add_f32_dpp %0, %0, %0 quad_perm:[1,0,3,2] row_mask:0xf bank_mask:0xf bound_ctrl:1\n\t"
;                 "v_add_f32_dpp %1, %1, %1 quad_perm:[1,0,3,2] row_mask:0xf bank_mask:0xf bound_ctrl:1\n\t"
;                 "s_nop 0\n\t"
;                 "v_add_f32_dpp %0, %0, %0 quad_perm:[2,3,0,1] row_mask:0xf bank_mask:0xf bound_ctrl:1\n\t"
;                 "v_add_f32_dpp %1, %1, %1 quad_perm:[2,3,0,1] row_mask:0xf bank_mask:0xf bound_ctrl:1\n\t"
;                 "s_nop 0\n\t"
;                 "v_add_f32_dpp %0, %0, %0 row_half_mirror row_mask:0xf bank_mask:0xf bound_ctrl:1\n\t"
;                 "v_add_f32_dpp %1, %1, %1 row_half_mirror row_mask:0xf bank_mask:0xf bound_ctrl:1"
;                 : "+v"(da), "+v"(dy));
;             {
;                 f32x2 t0;
;                 t0 = c[8].xy * v0; t0 = c[6].xy * da + t0; sp[0] = sp[0] * c[4].xy + t0;
;                 t0 = c[8].zw * v0; t0 = c[6].zw * da + t0; sp[1] = sp[1] * c[4].zw + t0;
;                 t0 = c[9].xy * v0; t0 = c[7].xy * da + t0; sp[2] = sp[2] * c[5].xy + t0;
;                 t0 = c[9].zw * v0; t0 = c[7].zw * da + t0; sp[3] = sp[3] * c[5].zw + t0;
;             }
;             ybb[t * 32] = dy + da * bk.x + v0 * bk.y;
	v_pk_mul_f32 v[122:123], v[38:39], v[42:43]
	v_pk_mul_f32 v[124:125], v[38:39], v[50:51]
	v_pk_fma_f32 v[122:123], v[36:37], v[40:41], v[122:123]
	v_pk_fma_f32 v[124:125], v[36:37], v[48:49], v[124:125]
	v_pk_fma_f32 v[122:123], v[32:33], v[44:45], v[122:123]
	v_pk_fma_f32 v[124:125], v[32:33], v[52:53], v[124:125]
	v_pk_fma_f32 v[122:123], v[34:35], v[46:47], v[122:123]
	v_pk_fma_f32 v[124:125], v[34:35], v[54:55], v[124:125]
	v_pk_mul_f32 v[126:127], v[72:73], v[94:95] op_sel_hi:[1,0]
	v_add_f32_e32 v166, v122, v123
	v_add_f32_e32 v168, v124, v125
	v_pk_mul_f32 v[128:129], v[74:75], v[94:95] op_sel_hi:[1,0]
	v_pk_mul_f32 v[130:131], v[76:77], v[94:95] op_sel_hi:[1,0]
	v_add_f32_dpp v166, v166, v166 quad_perm:[1,0,3,2] row_mask:0xf bank_mask:0xf bound_ctrl:1
	v_add_f32_dpp v168, v168, v168 quad_perm:[1,0,3,2] row_mask:0xf bank_mask:0xf bound_ctrl:1
	v_pk_mul_f32 v[132:133], v[78:79], v[94:95] op_sel_hi:[1,0]
	v_pk_fma_f32 v[126:127], v[36:37], v[56:57], v[126:127]
	v_add_f32_dpp v166, v166, v166 quad_perm:[2,3,0,1] row_mask:0xf bank_mask:0xf bound_ctrl:1
	v_add_f32_dpp v168, v168, v168 quad_perm:[2,3,0,1] row_mask:0xf bank_mask:0xf bound_ctrl:1
	v_pk_fma_f32 v[128:129], v[38:39], v[58:59], v[128:129]
	v_pk_fma_f32 v[130:131], v[32:33], v[60:61], v[130:131]
	v_add_f32_dpp v166, v166, v166 row_half_mirror row_mask:0xf bank_mask:0xf bound_ctrl:1
	v_add_f32_dpp v168, v168, v168 row_half_mirror row_mask:0xf bank_mask:0xf bound_ctrl:1
	v_pk_fma_f32 v[132:133], v[34:35], v[62:63], v[132:133]
	v_mov_b32_e32 v167, v94
	v_pk_mul_f32 v[134:135], v[166:167], v[108:109]
	v_pk_fma_f32 v[36:37], v[64:65], v[166:167], v[126:127] op_sel_hi:[1,0,1]
	v_pk_fma_f32 v[38:39], v[66:67], v[166:167], v[128:129] op_sel_hi:[1,0,1]
	v_pk_fma_f32 v[32:33], v[68:69], v[166:167], v[130:131] op_sel_hi:[1,0,1]
	v_pk_fma_f32 v[34:35], v[70:71], v[166:167], v[132:133] op_sel_hi:[1,0,1]
	v_add_f32_e32 v136, v168, v134
	v_add_f32_e32 v136, v135, v136
	ds_write_b32 v95, v136 offset:256
	ds_read_b128 v[40:43], v120 offset:5120
	ds_read_b128 v[44:47], v120 offset:5136
	ds_read_b128 v[48:51], v120 offset:5376
	ds_read_b128 v[52:55], v120 offset:5392
	ds_read_b128 v[56:59], v120 offset:5632
	ds_read_b128 v[60:63], v120 offset:5648
	ds_read_b128 v[64:67], v120 offset:5888
	ds_read_b128 v[68:71], v120 offset:5904
	ds_read_b128 v[72:75], v120 offset:6144
	ds_read_b128 v[76:79], v120 offset:6160
	ds_read_b32 v94, v96 offset:21504
	ds_read_b64 v[108:109], v121 offset:24640
	s_waitcnt lgkmcnt(12)
	v_pk_mul_f32 v[122:123], v[38:39], v[192:193]
	v_pk_mul_f32 v[124:125], v[38:39], v[200:201]
	v_pk_fma_f32 v[122:123], v[36:37], v[190:191], v[122:123]
	v_pk_fma_f32 v[124:125], v[36:37], v[198:199], v[124:125]
	v_pk_fma_f32 v[122:123], v[32:33], v[194:195], v[122:123]
	v_pk_fma_f32 v[124:125], v[32:33], v[202:203], v[124:125]
	v_pk_fma_f32 v[122:123], v[34:35], v[196:197], v[122:123]
	v_pk_fma_f32 v[124:125], v[34:35], v[204:205], v[124:125]
	v_pk_mul_f32 v[126:127], v[222:223], v[230:231] op_sel_hi:[1,0]
	v_add_f32_e32 v166, v122, v123
	v_add_f32_e32 v168, v124, v125
	v_pk_mul_f32 v[128:129], v[224:225], v[230:231] op_sel_hi:[1,0]
	v_pk_mul_f32 v[130:131], v[226:227], v[230:231] op_sel_hi:[1,0]
	v_add_f32_dpp v166, v166, v166 quad_perm:[1,0,3,2] row_mask:0xf bank_mask:0xf bound_ctrl:1
	v_add_f32_dpp v168, v168, v168 quad_perm:[1,0,3,2] row_mask:0xf bank_mask:0xf bound_ctrl:1
	v_pk_mul_f32 v[132:133], v[228:229], v[230:231] op_sel_hi:[1,0]
	v_pk_fma_f32 v[126:127], v[36:37], v[206:207], v[126:127]
	v_add_f32_dpp v166, v166, v166 quad_perm:[2,3,0,1] row_mask:0xf bank_mask:0xf bound_ctrl:1
	v_add_f32_dpp v168, v168, v168 quad_perm:[2,3,0,1] row_mask:0xf bank_mask:0xf bound_ctrl:1
	v_pk_fma_f32 v[128:129], v[38:39], v[208:209], v[128:129]
	v_pk_fma_f32 v[130:131], v[32:33], v[210:211], v[130:131]
	v_add_f32_dpp v166, v166, v166 row_half_mirror row_mask:0xf bank_mask:0xf bound_ctrl:1
	v_add_f32_dpp v168, v168, v168 row_half_mirror row_mask:0xf bank_mask:0xf bound_ctrl:1
	v_pk_fma_f32 v[132:133], v[34:35], v[212:213], v[132:133]
	v_mov_b32_e32 v167, v230
	v_pk_mul_f32 v[134:135], v[166:167], v[232:233]
	v_pk_fma_f32 v[36:37], v[214:215], v[166:167], v[126:127] op_sel_hi:[1,0,1]
	v_pk_fma_f32 v[38:39], v[216:217], v[166:167], v[128:129] op_sel_hi:[1,0,1]
	v_pk_fma_f32 v[32:33], v[218:219], v[166:167], v[130:131] op_sel_hi:[1,0,1]
	v_pk_fma_f32 v[34:35], v[220:221], v[166:167], v[132:133] op_sel_hi:[1,0,1]
	v_add_f32_e32 v136, v168, v134
	v_add_f32_e32 v136, v135, v136
	ds_write_b32 v95, v136 offset:384
	ds_read_b128 v[190:193], v120 offset:6400
	ds_read_b128 v[194:197], v120 offset:6416
	ds_read_b128 v[198:201], v120 offset:6656
	ds_read_b128 v[202:205], v120 offset:6672
	ds_read_b128 v[206:209], v120 offset:6912
	ds_read_b128 v[210:213], v120 offset:6928
	ds_read_b128 v[214:217], v120 offset:7168
	ds_read_b128 v[218:221], v120 offset:7184
	ds_read_b128 v[222:225], v120 offset:7424
	ds_read_b128 v[226:229], v120 offset:7440
	ds_read_b32 v230, v96 offset:21760
	ds_read_b64 v[232:233], v121 offset:24656
	s_waitcnt lgkmcnt(12)
; #define SC_LOAD(t) { _Pragma("unroll") for (int q = 0; q < 5; ++q) { n[2 * q] = *(const LAS f32x4*)(opb + (t) * 320 + q * 64); n[2 * q + 1] = *(const LAS f32x4*)(opb + (t) * 320 + q * 64 + 4); } \
;                      nv = vvb[(t) * 64]; nbk = *(const LAS f32x2*)(scb + (t) * 4); }
; DI void scan_item(const __attribute__((address_space(4))) Args& a, LAS unsigned char* lds, int ws_, bool is_prompt, int seq, int h, int half, bool dry = false) {
;     ...
; #pragma unroll 4
;         for (int t = 0; t < SC_CH; ++t) {
;             f32x4 c[10];
; #pragma unroll
;             for (int q = 0; q < 10; ++q) c[q] = n[q];
;             const float v0 = nv; const f32x2 bk = nbk;
;             SC_LOAD(t + 1)
;             __builtin_amdgcn_sched_barrier(0);
;             f32x2 aA = sp[0] * c[0].xy, aY = sp[0] * c[2].xy;
;             aA = sp[1] * c[0].zw + aA; aY = sp[1] * c[2].zw + aY;
;             aA = sp[2] * c[1].xy + aA; aY = sp[2] * c[3].xy + aY;
;             aA = sp[3] * c[1].zw + aA; aY = sp[3] * c[3].zw + aY;
;             float da = aA.x + aA.y, dy = aY.x + aY.y;
;             asm("s_nop 1\n\t"
;                 "v_add_f32_dpp %0, %0, %0 quad_perm:[1,0,3,2] row_mask:0xf bank_mask:0xf bound_ctrl:1\n\t"
;                 "v_add_f32_dpp %1, %1, %1 quad_perm:[1,0,3,2] row_mask:0xf bank_mask:0xf bound_ctrl:1\n\t"
;                 "s_nop 0\n\t"
;                 "v_add_f32_dpp %0, %0, %0 quad_perm:[2,3,0,1] row_mask:0xf bank_mask:0xf bound_ctrl:1\n\t"
;                 "v_add_f32_dpp %1, %1, %1 quad_perm:[2,3,0,1] row_mask:0xf bank_mask:0xf bound_ctrl:1\n\t"
;                 "s_nop 0\n\t"
;                 "v_add_f32_dpp %0, %0, %0 row_half_mirror row_mask:0xf bank_mask:0xf bound_ctrl:1\n\t"
;                 "v_add_f32_dpp %1, %1, %1 row_half_mirror row_mask:0xf bank_mask:0xf bound_ctrl:1"
;                 : "+v"(da), "+v"(dy));
;             {
;                 f32x2 t0;
;                 t0 = c[8].xy * v0; t0 = c[6].xy * da + t0; sp[0] = sp[0] * c[4].xy + t0;
;                 t0 = c[8].zw * v0; t0 = c[6].zw * da + t0; sp[1] = sp[1] * c[4].zw + t0;
;                 t0 = c[9].xy * v0; t0 = c[7].xy * da + t0; sp[2] = sp[2] * c[5].xy + t0;
;                 t0 = c[9].zw * v0; t0 = c[7].zw * da + t0; sp[3] = sp[3] * c[5].zw + t0;
;             }
;             ybb[t * 32] = dy + da * bk.x + v0 * bk.y;
	v_pk_mul_f32 v[122:123], v[38:39], v[42:43]
	v_pk_mul_f32 v[124:125], v[38:39], v[50:51]
	v_pk_fma_f32 v[122:123], v[36:37], v[40:41], v[122:123]
	v_pk_fma_f32 v[124:125], v[36:37], v[48:49], v[124:125]
	v_pk_fma_f32 v[122:123], v[32:33], v[44:45], v[122:123]
	v_pk_fma_f32 v[124:125], v[32:33], v[52:53], v[124:125]
	v_pk_fma_f32 v[122:123], v[34:35], v[46:47], v[122:123]
	v_pk_fma_f32 v[124:125], v[34:35], v[54:55], v[124:125]
	v_pk_mul_f32 v[126:127], v[72:73], v[94:95] op_sel_hi:[1,0]
	v_add_f32_e32 v166, v122, v123
	v_add_f32_e32 v168, v124, v125
	v_pk_mul_f32 v[128:129], v[74:75], v[94:95] op_sel_hi:[1,0]
	v_pk_mul_f32 v[130:131], v[76:77], v[94:95] op_sel_hi:[1,0]
	v_add_f32_dpp v166, v166, v166 quad_perm:[1,0,3,2] row_mask:0xf bank_mask:0xf bound_ctrl:1
	v_add_f32_dpp v168, v168, v168 quad_perm:[1,0,3,2] row_mask:0xf bank_mask:0xf bound_ctrl:1
	v_pk_mul_f32 v[132:133], v[78:79], v[94:95] op_sel_hi:[1,0]
	v_pk_fma_f32 v[126:127], v[36:37], v[56:57], v[126:127]
	v_add_f32_dpp v166, v166, v166 quad_perm:[2,3,0,1] row_mask:0xf bank_mask:0xf bound_ctrl:1
	v_add_f32_dpp v168, v168, v168 quad_perm:[2,3,0,1] row_mask:0xf bank_mask:0xf bound_ctrl:1
	v_pk_fma_f32 v[128:129], v[38:39], v[58:59], v[128:129]
	v_pk_fma_f32 v[130:131], v[32:33], v[60:61], v[130:131]
	v_add_f32_dpp v166, v166, v166 row_half_mirror row_mask:0xf bank_mask:0xf bound_ctrl:1
	v_add_f32_dpp v168, v168, v168 row_half_mirror row_mask:0xf bank_mask:0xf bound_ctrl:1
	v_pk_fma_f32 v[132:133], v[34:35], v[62:63], v[132:133]
	v_mov_b32_e32 v167, v94
	v_pk_mul_f32 v[134:135], v[166:167], v[108:109]
	v_pk_fma_f32 v[36:37], v[64:65], v[166:167], v[126:127] op_sel_hi:[1,0,1]
	v_pk_fma_f32 v[38:39], v[66:67], v[166:167], v[128:129] op_sel_hi:[1,0,1]
	v_pk_fma_f32 v[32:33], v[68:69], v[166:167], v[130:131] op_sel_hi:[1,0,1]
	v_pk_fma_f32 v[34:35], v[70:71], v[166:167], v[132:133] op_sel_hi:[1,0,1]
	v_add_f32_e32 v136, v168, v134
	v_add_f32_e32 v136, v135, v136
	ds_write_b32 v95, v136 offset:512
	ds_read_b128 v[40:43], v120 offset:7680
	ds_read_b128 v[44:47], v120 offset:7696
	ds_read_b128 v[48:51], v120 offset:7936
	ds_read_b128 v[52:55], v120 offset:7952
	ds_read_b128 v[56:59], v120 offset:8192
	ds_read_b128 v[60:63], v120 offset:8208
	ds_read_b128 v[64:67], v120 offset:8448
	ds_read_b128 v[68:71], v120 offset:8464
	ds_read_b128 v[72:75], v120 offset:8704
	ds_read_b128 v[76:79], v120 offset:8720
	ds_read_b32 v94, v96 offset:22016
	ds_read_b64 v[108:109], v121 offset:24672
	s_waitcnt lgkmcnt(12)
	v_pk_mul_f32 v[122:123], v[38:39], v[192:193]
	v_pk_mul_f32 v[124:125], v[38:39], v[200:201]
	v_pk_fma_f32 v[122:123], v[36:37], v[190:191], v[122:123]
	v_pk_fma_f32 v[124:125], v[36:37], v[198:199], v[124:125]
	v_pk_fma_f32 v[122:123], v[32:33], v[194:195], v[122:123]
	v_pk_fma_f32 v[124:125], v[32:33], v[202:203], v[124:125]
	v_pk_fma_f32 v[122:123], v[34:35], v[196:197], v[122:123]
	v_pk_fma_f32 v[124:125], v[34:35], v[204:205], v[124:125]
	v_pk_mul_f32 v[126:127], v[222:223], v[230:231] op_sel_hi:[1,0]
	v_add_f32_e32 v166, v122, v123
	v_add_f32_e32 v168, v124, v125
	v_pk_mul_f32 v[128:129], v[224:225], v[230:231] op_sel_hi:[1,0]
	v_pk_mul_f32 v[130:131], v[226:227], v[230:231] op_sel_hi:[1,0]
	v_add_f32_dpp v166, v166, v166 quad_perm:[1,0,3,2] row_mask:0xf bank_mask:0xf bound_ctrl:1
	v_add_f32_dpp v168, v168, v168 quad_perm:[1,0,3,2] row_mask:0xf bank_mask:0xf bound_ctrl:1
	v_pk_mul_f32 v[132:133], v[228:229], v[230:231] op_sel_hi:[1,0]
	v_pk_fma_f32 v[126:127], v[36:37], v[206:207], v[126:127]
	v_add_f32_dpp v166, v166, v166 quad_perm:[2,3,0,1] row_mask:0xf bank_mask:0xf bound_ctrl:1
	v_add_f32_dpp v168, v168, v168 quad_perm:[2,3,0,1] row_mask:0xf bank_mask:0xf bound_ctrl:1
	v_pk_fma_f32 v[128:129], v[38:39], v[208:209], v[128:129]
	v_pk_fma_f32 v[130:131], v[32:33], v[210:211], v[130:131]
	v_add_f32_dpp v166, v166, v166 row_half_mirror row_mask:0xf bank_mask:0xf bound_ctrl:1
	v_add_f32_dpp v168, v168, v168 row_half_mirror row_mask:0xf bank_mask:0xf bound_ctrl:1
	v_pk_fma_f32 v[132:133], v[34:35], v[212:213], v[132:133]
	v_mov_b32_e32 v167, v230
	v_pk_mul_f32 v[134:135], v[166:167], v[232:233]
	v_pk_fma_f32 v[36:37], v[214:215], v[166:167], v[126:127] op_sel_hi:[1,0,1]
	v_pk_fma_f32 v[38:39], v[216:217], v[166:167], v[128:129] op_sel_hi:[1,0,1]
	v_pk_fma_f32 v[32:33], v[218:219], v[166:167], v[130:131] op_sel_hi:[1,0,1]
	v_pk_fma_f32 v[34:35], v[220:221], v[166:167], v[132:133] op_sel_hi:[1,0,1]
	v_add_f32_e32 v136, v168, v134
	v_add_f32_e32 v136, v135, v136
	ds_write_b32 v95, v136 offset:640
	ds_read_b128 v[190:193], v120 offset:8960
	ds_read_b128 v[194:197], v120 offset:8976
	ds_read_b128 v[198:201], v120 offset:9216
	ds_read_b128 v[202:205], v120 offset:9232
	ds_read_b128 v[206:209], v120 offset:9472
	ds_read_b128 v[210:213], v120 offset:9488
	ds_read_b128 v[214:217], v120 offset:9728
	ds_read_b128 v[218:221], v120 offset:9744
	ds_read_b128 v[222:225], v120 offset:9984
	ds_read_b128 v[226:229], v120 offset:10000
	ds_read_b32 v230, v96 offset:22272
	ds_read_b64 v[232:233], v121 offset:24688
	s_waitcnt lgkmcnt(12)
; #define SC_LOAD(t) { _Pragma("unroll") for (int q = 0; q < 5; ++q) { n[2 * q] = *(const LAS f32x4*)(opb + (t) * 320 + q * 64); n[2 * q + 1] = *(const LAS f32x4*)(opb + (t) * 320 + q * 64 + 4); } \
;                      nv = vvb[(t) * 64]; nbk = *(const LAS f32x2*)(scb + (t) * 4); }
; DI void scan_item(const __attribute__((address_space(4))) Args& a, LAS unsigned char* lds, int ws_, bool is_prompt, int seq, int h, int half, bool dry = false) {
;     ...
; #pragma unroll 4
;         for (int t = 0; t < SC_CH; ++t) {
;             f32x4 c[10];
; #pragma unroll
;             for (int q = 0; q < 10; ++q) c[q] = n[q];
;             const float v0 = nv; const f32x2 bk = nbk;
;             SC_LOAD(t + 1)
;             __builtin_amdgcn_sched_barrier(0);
;             f32x2 aA = sp[0] * c[0].xy, aY = sp[0] * c[2].xy;
;             aA = sp[1] * c[0].zw + aA; aY = sp[1] * c[2].zw + aY;
;             aA = sp[2] * c[1].xy + aA; aY = sp[2] * c[3].xy + aY;
;             aA = sp[3] * c[1].zw + aA; aY = sp[3] * c[3].zw + aY;
;             float da = aA.x + aA.y, dy = aY.x + aY.y;
;             asm("s_nop 1\n\t"
;                 "v_add_f32_dpp %0, %0, %0 quad_perm:[1,0,3,2] row_mask:0xf bank_mask:0xf bound_ctrl:1\n\t"
;                 "v_add_f32_dpp %1, %1, %1 quad_perm:[1,0,3,2] row_mask:0xf bank_mask:0xf bound_ctrl:1\n\t"
;                 "s_nop 0\n\t"
;                 "v_add_f32_dpp %0, %0, %0 quad_perm:[2,3,0,1] row_mask:0xf bank_mask:0xf bound_ctrl:1\n\t"
;                 "v_add_f32_dpp %1, %1, %1 quad_perm:[2,3,0,1] row_mask:0xf bank_mask:0xf bound_ctrl:1\n\t"
;                 "s_nop 0\n\t"
;                 "v_add_f32_dpp %0, %0, %0 row_half_mirror row_mask:0xf bank_mask:0xf bound_ctrl:1\n\t"
;                 "v_add_f32_dpp %1, %1, %1 row_half_mirror row_mask:0xf bank_mask:0xf bound_ctrl:1"
;                 : "+v"(da), "+v"(dy));
;             {
;                 f32x2 t0;
;                 t0 = c[8].xy * v0; t0 = c[6].xy * da + t0; sp[0] = sp[0] * c[4].xy + t0;
;                 t0 = c[8].zw * v0; t0 = c[6].zw * da + t0; sp[1] = sp[1] * c[4].zw + t0;
;                 t0 = c[9].xy * v0; t0 = c[7].xy * da + t0; sp[2] = sp[2] * c[5].xy + t0;
;                 t0 = c[9].zw * v0; t0 = c[7].zw * da + t0; sp[3] = sp[3] * c[5].zw + t0;
;             }
;             ybb[t * 32] = dy + da * bk.x + v0 * bk.y;
	v_pk_mul_f32 v[122:123], v[38:39], v[42:43]
	v_pk_mul_f32 v[124:125], v[38:39], v[50:51]
	v_pk_fma_f32 v[122:123], v[36:37], v[40:41], v[122:123]
	v_pk_fma_f32 v[124:125], v[36:37], v[48:49], v[124:125]
	v_pk_fma_f32 v[122:123], v[32:33], v[44:45], v[122:123]
	v_pk_fma_f32 v[124:125], v[32:33], v[52:53], v[124:125]
	v_pk_fma_f32 v[122:123], v[34:35], v[46:47], v[122:123]
	v_pk_fma_f32 v[124:125], v[34:35], v[54:55], v[124:125]
	v_pk_mul_f32 v[126:127], v[72:73], v[94:95] op_sel_hi:[1,0]
	v_add_f32_e32 v166, v122, v123
	v_add_f32_e32 v168, v124, v125
	v_pk_mul_f32 v[128:129], v[74:75], v[94:95] op_sel_hi:[1,0]
	v_pk_mul_f32 v[130:131], v[76:77], v[94:95] op_sel_hi:[1,0]
	v_add_f32_dpp v166, v166, v166 quad_perm:[1,0,3,2] row_mask:0xf bank_mask:0xf bound_ctrl:1
	v_add_f32_dpp v168, v168, v168 quad_perm:[1,0,3,2] row_mask:0xf bank_mask:0xf bound_ctrl:1
	v_pk_mul_f32 v[132:133], v[78:79], v[94:95] op_sel_hi:[1,0]
	v_pk_fma_f32 v[126:127], v[36:37], v[56:57], v[126:127]
	v_add_f32_dpp v166, v166, v166 quad_perm:[2,3,0,1] row_mask:0xf bank_mask:0xf bound_ctrl:1
	v_add_f32_dpp v168, v168, v168 quad_perm:[2,3,0,1] row_mask:0xf bank_mask:0xf bound_ctrl:1
	v_pk_fma_f32 v[128:129], v[38:39], v[58:59], v[128:129]
	v_pk_fma_f32 v[130:131], v[32:33], v[60:61], v[130:131]
	v_add_f32_dpp v166, v166, v166 row_half_mirror row_mask:0xf bank_mask:0xf bound_ctrl:1
	v_add_f32_dpp v168, v168, v168 row_half_mirror row_mask:0xf bank_mask:0xf bound_ctrl:1
	v_pk_fma_f32 v[132:133], v[34:35], v[62:63], v[132:133]
	v_mov_b32_e32 v167, v94
	v_pk_mul_f32 v[134:135], v[166:167], v[108:109]
	v_pk_fma_f32 v[36:37], v[64:65], v[166:167], v[126:127] op_sel_hi:[1,0,1]
	v_pk_fma_f32 v[38:39], v[66:67], v[166:167], v[128:129] op_sel_hi:[1,0,1]
	v_pk_fma_f32 v[32:33], v[68:69], v[166:167], v[130:131] op_sel_hi:[1,0,1]
	v_pk_fma_f32 v[34:35], v[70:71], v[166:167], v[132:133] op_sel_hi:[1,0,1]
	v_add_f32_e32 v136, v168, v134
	v_add_f32_e32 v136, v135, v136
	ds_write_b32 v95, v136 offset:768
	ds_read_b128 v[40:43], v120 offset:10240
	ds_read_b128 v[44:47], v120 offset:10256
	ds_read_b128 v[48:51], v120 offset:10496
	ds_read_b128 v[52:55], v120 offset:10512
	ds_read_b128 v[56:59], v120 offset:10752
	ds_read_b128 v[60:63], v120 offset:10768
	ds_read_b128 v[64:67], v120 offset:11008
	ds_read_b128 v[68:71], v120 offset:11024
	ds_read_b128 v[72:75], v120 offset:11264
	ds_read_b128 v[76:79], v120 offset:11280
	ds_read_b32 v94, v96 offset:22528
	ds_read_b64 v[108:109], v121 offset:24704
	s_waitcnt lgkmcnt(12)
	v_pk_mul_f32 v[122:123], v[38:39], v[192:193]
	v_pk_mul_f32 v[124:125], v[38:39], v[200:201]
	v_pk_fma_f32 v[122:123], v[36:37], v[190:191], v[122:123]
	v_pk_fma_f32 v[124:125], v[36:37], v[198:199], v[124:125]
	v_pk_fma_f32 v[122:123], v[32:33], v[194:195], v[122:123]
	v_pk_fma_f32 v[124:125], v[32:33], v[202:203], v[124:125]
	v_pk_fma_f32 v[122:123], v[34:35], v[196:197], v[122:123]
	v_pk_fma_f32 v[124:125], v[34:35], v[204:205], v[124:125]
	v_pk_mul_f32 v[126:127], v[222:223], v[230:231] op_sel_hi:[1,0]
	v_add_f32_e32 v166, v122, v123
	v_add_f32_e32 v168, v124, v125
	v_pk_mul_f32 v[128:129], v[224:225], v[230:231] op_sel_hi:[1,0]
	v_pk_mul_f32 v[130:131], v[226:227], v[230:231] op_sel_hi:[1,0]
	v_add_f32_dpp v166, v166, v166 quad_perm:[1,0,3,2] row_mask:0xf bank_mask:0xf bound_ctrl:1
	v_add_f32_dpp v168, v168, v168 quad_perm:[1,0,3,2] row_mask:0xf bank_mask:0xf bound_ctrl:1
	v_pk_mul_f32 v[132:133], v[228:229], v[230:231] op_sel_hi:[1,0]
	v_pk_fma_f32 v[126:127], v[36:37], v[206:207], v[126:127]
	v_add_f32_dpp v166, v166, v166 quad_perm:[2,3,0,1] row_mask:0xf bank_mask:0xf bound_ctrl:1
	v_add_f32_dpp v168, v168, v168 quad_perm:[2,3,0,1] row_mask:0xf bank_mask:0xf bound_ctrl:1
	v_pk_fma_f32 v[128:129], v[38:39], v[208:209], v[128:129]
	v_pk_fma_f32 v[130:131], v[32:33], v[210:211], v[130:131]
	v_add_f32_dpp v166, v166, v166 row_half_mirror row_mask:0xf bank_mask:0xf bound_ctrl:1
	v_add_f32_dpp v168, v168, v168 row_half_mirror row_mask:0xf bank_mask:0xf bound_ctrl:1
	v_pk_fma_f32 v[132:133], v[34:35], v[212:213], v[132:133]
	v_mov_b32_e32 v167, v230
	v_pk_mul_f32 v[134:135], v[166:167], v[232:233]
	v_pk_fma_f32 v[36:37], v[214:215], v[166:167], v[126:127] op_sel_hi:[1,0,1]
	v_pk_fma_f32 v[38:39], v[216:217], v[166:167], v[128:129] op_sel_hi:[1,0,1]
	v_pk_fma_f32 v[32:33], v[218:219], v[166:167], v[130:131] op_sel_hi:[1,0,1]
	v_pk_fma_f32 v[34:35], v[220:221], v[166:167], v[132:133] op_sel_hi:[1,0,1]
	v_add_f32_e32 v136, v168, v134
	v_add_f32_e32 v136, v135, v136
	ds_write_b32 v95, v136 offset:896
	ds_read_b128 v[190:193], v120 offset:11520
	ds_read_b128 v[194:197], v120 offset:11536
	ds_read_b128 v[198:201], v120 offset:11776
	ds_read_b128 v[202:205], v120 offset:11792
	ds_read_b128 v[206:209], v120 offset:12032
	ds_read_b128 v[210:213], v120 offset:12048
	ds_read_b128 v[214:217], v120 offset:12288
	ds_read_b128 v[218:221], v120 offset:12304
	ds_read_b128 v[222:225], v120 offset:12544
	ds_read_b128 v[226:229], v120 offset:12560
	ds_read_b32 v230, v96 offset:22784
	ds_read_b64 v[232:233], v121 offset:24720
	s_waitcnt lgkmcnt(12)
; #define SC_LOAD(t) { _Pragma("unroll") for (int q = 0; q < 5; ++q) { n[2 * q] = *(const LAS f32x4*)(opb + (t) * 320 + q * 64); n[2 * q + 1] = *(const LAS f32x4*)(opb + (t) * 320 + q * 64 + 4); } \
;                      nv = vvb[(t) * 64]; nbk = *(const LAS f32x2*)(scb + (t) * 4); }
; DI void scan_item(const __attribute__((address_space(4))) Args& a, LAS unsigned char* lds, int ws_, bool is_prompt, int seq, int h, int half, bool dry = false) {
;     ...
; #pragma unroll 4
;         for (int t = 0; t < SC_CH; ++t) {
;             f32x4 c[10];
; #pragma unroll
;             for (int q = 0; q < 10; ++q) c[q] = n[q];
;             const float v0 = nv; const f32x2 bk = nbk;
;             SC_LOAD(t + 1)
;             __builtin_amdgcn_sched_barrier(0);
;             f32x2 aA = sp[0] * c[0].xy, aY = sp[0] * c[2].xy;
;             aA = sp[1] * c[0].zw + aA; aY = sp[1] * c[2].zw + aY;
;             aA = sp[2] * c[1].xy + aA; aY = sp[2] * c[3].xy + aY;
;             aA = sp[3] * c[1].zw + aA; aY = sp[3] * c[3].zw + aY;
;             float da = aA.x + aA.y, dy = aY.x + aY.y;
;             asm("s_nop 1\n\t"
;                 "v_add_f32_dpp %0, %0, %0 quad_perm:[1,0,3,2] row_mask:0xf bank_mask:0xf bound_ctrl:1\n\t"
;                 "v_add_f32_dpp %1, %1, %1 quad_perm:[1,0,3,2] row_mask:0xf bank_mask:0xf bound_ctrl:1\n\t"
;                 "s_nop 0\n\t"
;                 "v_add_f32_dpp %0, %0, %0 quad_perm:[2,3,0,1] row_mask:0xf bank_mask:0xf bound_ctrl:1\n\t"
;                 "v_add_f32_dpp %1, %1, %1 quad_perm:[2,3,0,1] row_mask:0xf bank_mask:0xf bound_ctrl:1\n\t"
;                 "s_nop 0\n\t"
;                 "v_add_f32_dpp %0, %0, %0 row_half_mirror row_mask:0xf bank_mask:0xf bound_ctrl:1\n\t"
;                 "v_add_f32_dpp %1, %1, %1 row_half_mirror row_mask:0xf bank_mask:0xf bound_ctrl:1"
;                 : "+v"(da), "+v"(dy));
;             {
;                 f32x2 t0;
;                 t0 = c[8].xy * v0; t0 = c[6].xy * da + t0; sp[0] = sp[0] * c[4].xy + t0;
;                 t0 = c[8].zw * v0; t0 = c[6].zw * da + t0; sp[1] = sp[1] * c[4].zw + t0;
;                 t0 = c[9].xy * v0; t0 = c[7].xy * da + t0; sp[2] = sp[2] * c[5].xy + t0;
;                 t0 = c[9].zw * v0; t0 = c[7].zw * da + t0; sp[3] = sp[3] * c[5].zw + t0;
;             }
;             ybb[t * 32] = dy + da * bk.x + v0 * bk.y;
	v_pk_mul_f32 v[122:123], v[38:39], v[42:43]
	v_pk_mul_f32 v[124:125], v[38:39], v[50:51]
	v_pk_fma_f32 v[122:123], v[36:37], v[40:41], v[122:123]
	v_pk_fma_f32 v[124:125], v[36:37], v[48:49], v[124:125]
	v_pk_fma_f32 v[122:123], v[32:33], v[44:45], v[122:123]
	v_pk_fma_f32 v[124:125], v[32:33], v[52:53], v[124:125]
	v_pk_fma_f32 v[122:123], v[34:35], v[46:47], v[122:123]
	v_pk_fma_f32 v[124:125], v[34:35], v[54:55], v[124:125]
	v_pk_mul_f32 v[126:127], v[72:73], v[94:95] op_sel_hi:[1,0]
	v_add_f32_e32 v166, v122, v123
	v_add_f32_e32 v168, v124, v125
	v_pk_mul_f32 v[128:129], v[74:75], v[94:95] op_sel_hi:[1,0]
	v_pk_mul_f32 v[130:131], v[76:77], v[94:95] op_sel_hi:[1,0]
	v_add_f32_dpp v166, v166, v166 quad_perm:[1,0,3,2] row_mask:0xf bank_mask:0xf bound_ctrl:1
	v_add_f32_dpp v168, v168, v168 quad_perm:[1,0,3,2] row_mask:0xf bank_mask:0xf bound_ctrl:1
	v_pk_mul_f32 v[132:133], v[78:79], v[94:95] op_sel_hi:[1,0]
	v_pk_fma_f32 v[126:127], v[36:37], v[56:57], v[126:127]
	v_add_f32_dpp v166, v166, v166 quad_perm:[2,3,0,1] row_mask:0xf bank_mask:0xf bound_ctrl:1
	v_add_f32_dpp v168, v168, v168 quad_perm:[2,3,0,1] row_mask:0xf bank_mask:0xf bound_ctrl:1
	v_pk_fma_f32 v[128:129], v[38:39], v[58:59], v[128:129]
	v_pk_fma_f32 v[130:131], v[32:33], v[60:61], v[130:131]
	v_add_f32_dpp v166, v166, v166 row_half_mirror row_mask:0xf bank_mask:0xf bound_ctrl:1
	v_add_f32_dpp v168, v168, v168 row_half_mirror row_mask:0xf bank_mask:0xf bound_ctrl:1
	v_pk_fma_f32 v[132:133], v[34:35], v[62:63], v[132:133]
	v_mov_b32_e32 v167, v94
	v_pk_mul_f32 v[134:135], v[166:167], v[108:109]
	v_pk_fma_f32 v[36:37], v[64:65], v[166:167], v[126:127] op_sel_hi:[1,0,1]
	v_pk_fma_f32 v[38:39], v[66:67], v[166:167], v[128:129] op_sel_hi:[1,0,1]
	v_pk_fma_f32 v[32:33], v[68:69], v[166:167], v[130:131] op_sel_hi:[1,0,1]
	v_pk_fma_f32 v[34:35], v[70:71], v[166:167], v[132:133] op_sel_hi:[1,0,1]
	v_add_f32_e32 v136, v168, v134
	v_add_f32_e32 v136, v135, v136
	ds_write_b32 v95, v136 offset:1024
	ds_read_b128 v[40:43], v120 offset:12800
	ds_read_b128 v[44:47], v120 offset:12816
	ds_read_b128 v[48:51], v120 offset:13056
	ds_read_b128 v[52:55], v120 offset:13072
	ds_read_b128 v[56:59], v120 offset:13312
	ds_read_b128 v[60:63], v120 offset:13328
	ds_read_b128 v[64:67], v120 offset:13568
	ds_read_b128 v[68:71], v120 offset:13584
	ds_read_b128 v[72:75], v120 offset:13824
	ds_read_b128 v[76:79], v120 offset:13840
	ds_read_b32 v94, v96 offset:23040
	ds_read_b64 v[108:109], v121 offset:24736
	s_waitcnt lgkmcnt(12)
	v_pk_mul_f32 v[122:123], v[38:39], v[192:193]
	v_pk_mul_f32 v[124:125], v[38:39], v[200:201]
	v_pk_fma_f32 v[122:123], v[36:37], v[190:191], v[122:123]
	v_pk_fma_f32 v[124:125], v[36:37], v[198:199], v[124:125]
	v_pk_fma_f32 v[122:123], v[32:33], v[194:195], v[122:123]
	v_pk_fma_f32 v[124:125], v[32:33], v[202:203], v[124:125]
	v_pk_fma_f32 v[122:123], v[34:35], v[196:197], v[122:123]
	v_pk_fma_f32 v[124:125], v[34:35], v[204:205], v[124:125]
	v_pk_mul_f32 v[126:127], v[222:223], v[230:231] op_sel_hi:[1,0]
	v_add_f32_e32 v166, v122, v123
	v_add_f32_e32 v168, v124, v125
	v_pk_mul_f32 v[128:129], v[224:225], v[230:231] op_sel_hi:[1,0]
	v_pk_mul_f32 v[130:131], v[226:227], v[230:231] op_sel_hi:[1,0]
	v_add_f32_dpp v166, v166, v166 quad_perm:[1,0,3,2] row_mask:0xf bank_mask:0xf bound_ctrl:1
	v_add_f32_dpp v168, v168, v168 quad_perm:[1,0,3,2] row_mask:0xf bank_mask:0xf bound_ctrl:1
	v_pk_mul_f32 v[132:133], v[228:229], v[230:231] op_sel_hi:[1,0]
	v_pk_fma_f32 v[126:127], v[36:37], v[206:207], v[126:127]
	v_add_f32_dpp v166, v166, v166 quad_perm:[2,3,0,1] row_mask:0xf bank_mask:0xf bound_ctrl:1
	v_add_f32_dpp v168, v168, v168 quad_perm:[2,3,0,1] row_mask:0xf bank_mask:0xf bound_ctrl:1
	v_pk_fma_f32 v[128:129], v[38:39], v[208:209], v[128:129]
	v_pk_fma_f32 v[130:131], v[32:33], v[210:211], v[130:131]
	v_add_f32_dpp v166, v166, v166 row_half_mirror row_mask:0xf bank_mask:0xf bound_ctrl:1
	v_add_f32_dpp v168, v168, v168 row_half_mirror row_mask:0xf bank_mask:0xf bound_ctrl:1
	v_pk_fma_f32 v[132:133], v[34:35], v[212:213], v[132:133]
	v_mov_b32_e32 v167, v230
	v_pk_mul_f32 v[134:135], v[166:167], v[232:233]
	v_pk_fma_f32 v[36:37], v[214:215], v[166:167], v[126:127] op_sel_hi:[1,0,1]
	v_pk_fma_f32 v[38:39], v[216:217], v[166:167], v[128:129] op_sel_hi:[1,0,1]
	v_pk_fma_f32 v[32:33], v[218:219], v[166:167], v[130:131] op_sel_hi:[1,0,1]
	v_pk_fma_f32 v[34:35], v[220:221], v[166:167], v[132:133] op_sel_hi:[1,0,1]
	v_add_f32_e32 v136, v168, v134
	v_add_f32_e32 v136, v135, v136
	ds_write_b32 v95, v136 offset:1152
	ds_read_b128 v[190:193], v120 offset:14080
	ds_read_b128 v[194:197], v120 offset:14096
	ds_read_b128 v[198:201], v120 offset:14336
	ds_read_b128 v[202:205], v120 offset:14352
	ds_read_b128 v[206:209], v120 offset:14592
	ds_read_b128 v[210:213], v120 offset:14608
	ds_read_b128 v[214:217], v120 offset:14848
	ds_read_b128 v[218:221], v120 offset:14864
	ds_read_b128 v[222:225], v120 offset:15104
	ds_read_b128 v[226:229], v120 offset:15120
	ds_read_b32 v230, v96 offset:23296
	ds_read_b64 v[232:233], v121 offset:24752
	s_waitcnt lgkmcnt(12)
; #define SC_LOAD(t) { _Pragma("unroll") for (int q = 0; q < 5; ++q) { n[2 * q] = *(const LAS f32x4*)(opb + (t) * 320 + q * 64); n[2 * q + 1] = *(const LAS f32x4*)(opb + (t) * 320 + q * 64 + 4); } \
;                      nv = vvb[(t) * 64]; nbk = *(const LAS f32x2*)(scb + (t) * 4); }
; DI void scan_item(const __attribute__((address_space(4))) Args& a, LAS unsigned char* lds, int ws_, bool is_prompt, int seq, int h, int half, bool dry = false) {
;     ...
; #pragma unroll 4
;         for (int t = 0; t < SC_CH; ++t) {
;             f32x4 c[10];
; #pragma unroll
;             for (int q = 0; q < 10; ++q) c[q] = n[q];
;             const float v0 = nv; const f32x2 bk = nbk;
;             SC_LOAD(t + 1)
;             __builtin_amdgcn_sched_barrier(0);
;             f32x2 aA = sp[0] * c[0].xy, aY = sp[0] * c[2].xy;
;             aA = sp[1] * c[0].zw + aA; aY = sp[1] * c[2].zw + aY;
;             aA = sp[2] * c[1].xy + aA; aY = sp[2] * c[3].xy + aY;
;             aA = sp[3] * c[1].zw + aA; aY = sp[3] * c[3].zw + aY;
;             float da = aA.x + aA.y, dy = aY.x + aY.y;
;             asm("s_nop 1\n\t"
;                 "v_add_f32_dpp %0, %0, %0 quad_perm:[1,0,3,2] row_mask:0xf bank_mask:0xf bound_ctrl:1\n\t"
;                 "v_add_f32_dpp %1, %1, %1 quad_perm:[1,0,3,2] row_mask:0xf bank_mask:0xf bound_ctrl:1\n\t"
;                 "s_nop 0\n\t"
;                 "v_add_f32_dpp %0, %0, %0 quad_perm:[2,3,0,1] row_mask:0xf bank_mask:0xf bound_ctrl:1\n\t"
;                 "v_add_f32_dpp %1, %1, %1 quad_perm:[2,3,0,1] row_mask:0xf bank_mask:0xf bound_ctrl:1\n\t"
;                 "s_nop 0\n\t"
;                 "v_add_f32_dpp %0, %0, %0 row_half_mirror row_mask:0xf bank_mask:0xf bound_ctrl:1\n\t"
;                 "v_add_f32_dpp %1, %1, %1 row_half_mirror row_mask:0xf bank_mask:0xf bound_ctrl:1"
;                 : "+v"(da), "+v"(dy));
;             {
;                 f32x2 t0;
;                 t0 = c[8].xy * v0; t0 = c[6].xy * da + t0; sp[0] = sp[0] * c[4].xy + t0;
;                 t0 = c[8].zw * v0; t0 = c[6].zw * da + t0; sp[1] = sp[1] * c[4].zw + t0;
;                 t0 = c[9].xy * v0; t0 = c[7].xy * da + t0; sp[2] = sp[2] * c[5].xy + t0;
;                 t0 = c[9].zw * v0; t0 = c[7].zw * da + t0; sp[3] = sp[3] * c[5].zw + t0;
;             }
;             ybb[t * 32] = dy + da * bk.x + v0 * bk.y;
	v_pk_mul_f32 v[122:123], v[38:39], v[42:43]
	v_pk_mul_f32 v[124:125], v[38:39], v[50:51]
	v_pk_fma_f32 v[122:123], v[36:37], v[40:41], v[122:123]
	v_pk_fma_f32 v[124:125], v[36:37], v[48:49], v[124:125]
	v_pk_fma_f32 v[122:123], v[32:33], v[44:45], v[122:123]
	v_pk_fma_f32 v[124:125], v[32:33], v[52:53], v[124:125]
	v_pk_fma_f32 v[122:123], v[34:35], v[46:47], v[122:123]
	v_pk_fma_f32 v[124:125], v[34:35], v[54:55], v[124:125]
	v_pk_mul_f32 v[126:127], v[72:73], v[94:95] op_sel_hi:[1,0]
	v_add_f32_e32 v166, v122, v123
	v_add_f32_e32 v168, v124, v125
	v_pk_mul_f32 v[128:129], v[74:75], v[94:95] op_sel_hi:[1,0]
	v_pk_mul_f32 v[130:131], v[76:77], v[94:95] op_sel_hi:[1,0]
	v_add_f32_dpp v166, v166, v166 quad_perm:[1,0,3,2] row_mask:0xf bank_mask:0xf bound_ctrl:1
	v_add_f32_dpp v168, v168, v168 quad_perm:[1,0,3,2] row_mask:0xf bank_mask:0xf bound_ctrl:1
	v_pk_mul_f32 v[132:133], v[78:79], v[94:95] op_sel_hi:[1,0]
	v_pk_fma_f32 v[126:127], v[36:37], v[56:57], v[126:127]
	v_add_f32_dpp v166, v166, v166 quad_perm:[2,3,0,1] row_mask:0xf bank_mask:0xf bound_ctrl:1
	v_add_f32_dpp v168, v168, v168 quad_perm:[2,3,0,1] row_mask:0xf bank_mask:0xf bound_ctrl:1
	v_pk_fma_f32 v[128:129], v[38:39], v[58:59], v[128:129]
	v_pk_fma_f32 v[130:131], v[32:33], v[60:61], v[130:131]
	v_add_f32_dpp v166, v166, v166 row_half_mirror row_mask:0xf bank_mask:0xf bound_ctrl:1
	v_add_f32_dpp v168, v168, v168 row_half_mirror row_mask:0xf bank_mask:0xf bound_ctrl:1
	v_pk_fma_f32 v[132:133], v[34:35], v[62:63], v[132:133]
	v_mov_b32_e32 v167, v94
	v_pk_mul_f32 v[134:135], v[166:167], v[108:109]
	v_pk_fma_f32 v[36:37], v[64:65], v[166:167], v[126:127] op_sel_hi:[1,0,1]
	v_pk_fma_f32 v[38:39], v[66:67], v[166:167], v[128:129] op_sel_hi:[1,0,1]
	v_pk_fma_f32 v[32:33], v[68:69], v[166:167], v[130:131] op_sel_hi:[1,0,1]
	v_pk_fma_f32 v[34:35], v[70:71], v[166:167], v[132:133] op_sel_hi:[1,0,1]
	v_add_f32_e32 v136, v168, v134
	v_add_f32_e32 v136, v135, v136
	ds_write_b32 v95, v136 offset:1280
	ds_read_b128 v[40:43], v120 offset:15360
	ds_read_b128 v[44:47], v120 offset:15376
	ds_read_b128 v[48:51], v120 offset:15616
	ds_read_b128 v[52:55], v120 offset:15632
	ds_read_b128 v[56:59], v120 offset:15872
	ds_read_b128 v[60:63], v120 offset:15888
	ds_read_b128 v[64:67], v120 offset:16128
	ds_read_b128 v[68:71], v120 offset:16144
	ds_read_b128 v[72:75], v120 offset:16384
	ds_read_b128 v[76:79], v120 offset:16400
	ds_read_b32 v94, v96 offset:23552
	ds_read_b64 v[108:109], v121 offset:24768
	s_waitcnt lgkmcnt(12)
	v_pk_mul_f32 v[122:123], v[38:39], v[192:193]
	v_pk_mul_f32 v[124:125], v[38:39], v[200:201]
	v_pk_fma_f32 v[122:123], v[36:37], v[190:191], v[122:123]
	v_pk_fma_f32 v[124:125], v[36:37], v[198:199], v[124:125]
	v_pk_fma_f32 v[122:123], v[32:33], v[194:195], v[122:123]
	v_pk_fma_f32 v[124:125], v[32:33], v[202:203], v[124:125]
	v_pk_fma_f32 v[122:123], v[34:35], v[196:197], v[122:123]
	v_pk_fma_f32 v[124:125], v[34:35], v[204:205], v[124:125]
	v_pk_mul_f32 v[126:127], v[222:223], v[230:231] op_sel_hi:[1,0]
	v_add_f32_e32 v166, v122, v123
	v_add_f32_e32 v168, v124, v125
	v_pk_mul_f32 v[128:129], v[224:225], v[230:231] op_sel_hi:[1,0]
	v_pk_mul_f32 v[130:131], v[226:227], v[230:231] op_sel_hi:[1,0]
	v_add_f32_dpp v166, v166, v166 quad_perm:[1,0,3,2] row_mask:0xf bank_mask:0xf bound_ctrl:1
	v_add_f32_dpp v168, v168, v168 quad_perm:[1,0,3,2] row_mask:0xf bank_mask:0xf bound_ctrl:1
	v_pk_mul_f32 v[132:133], v[228:229], v[230:231] op_sel_hi:[1,0]
	v_pk_fma_f32 v[126:127], v[36:37], v[206:207], v[126:127]
	v_add_f32_dpp v166, v166, v166 quad_perm:[2,3,0,1] row_mask:0xf bank_mask:0xf bound_ctrl:1
	v_add_f32_dpp v168, v168, v168 quad_perm:[2,3,0,1] row_mask:0xf bank_mask:0xf bound_ctrl:1
	v_pk_fma_f32 v[128:129], v[38:39], v[208:209], v[128:129]
	v_pk_fma_f32 v[130:131], v[32:33], v[210:211], v[130:131]
	v_add_f32_dpp v166, v166, v166 row_half_mirror row_mask:0xf bank_mask:0xf bound_ctrl:1
	v_add_f32_dpp v168, v168, v168 row_half_mirror row_mask:0xf bank_mask:0xf bound_ctrl:1
	v_pk_fma_f32 v[132:133], v[34:35], v[212:213], v[132:133]
	v_mov_b32_e32 v167, v230
	v_pk_mul_f32 v[134:135], v[166:167], v[232:233]
	v_pk_fma_f32 v[36:37], v[214:215], v[166:167], v[126:127] op_sel_hi:[1,0,1]
	v_pk_fma_f32 v[38:39], v[216:217], v[166:167], v[128:129] op_sel_hi:[1,0,1]
	v_pk_fma_f32 v[32:33], v[218:219], v[166:167], v[130:131] op_sel_hi:[1,0,1]
	v_pk_fma_f32 v[34:35], v[220:221], v[166:167], v[132:133] op_sel_hi:[1,0,1]
	v_add_f32_e32 v136, v168, v134
	v_add_f32_e32 v136, v135, v136
	ds_write_b32 v95, v136 offset:1408
	ds_read_b128 v[190:193], v120 offset:16640
	ds_read_b128 v[194:197], v120 offset:16656
	ds_read_b128 v[198:201], v120 offset:16896
	ds_read_b128 v[202:205], v120 offset:16912
	ds_read_b128 v[206:209], v120 offset:17152
	ds_read_b128 v[210:213], v120 offset:17168
	ds_read_b128 v[214:217], v120 offset:17408
	ds_read_b128 v[218:221], v120 offset:17424
	ds_read_b128 v[222:225], v120 offset:17664
	ds_read_b128 v[226:229], v120 offset:17680
	ds_read_b32 v230, v96 offset:23808
	ds_read_b64 v[232:233], v121 offset:24784
	s_waitcnt lgkmcnt(12)
; #define SC_LOAD(t) { _Pragma("unroll") for (int q = 0; q < 5; ++q) { n[2 * q] = *(const LAS f32x4*)(opb + (t) * 320 + q * 64); n[2 * q + 1] = *(const LAS f32x4*)(opb + (t) * 320 + q * 64 + 4); } \
;                      nv = vvb[(t) * 64]; nbk = *(const LAS f32x2*)(scb + (t) * 4); }
; DI void scan_item(const __attribute__((address_space(4))) Args& a, LAS unsigned char* lds, int ws_, bool is_prompt, int seq, int h, int half, bool dry = false) {
;     ...
; #pragma unroll 4
;         for (int t = 0; t < SC_CH; ++t) {
;             f32x4 c[10];
; #pragma unroll
;             for (int q = 0; q < 10; ++q) c[q] = n[q];
;             const float v0 = nv; const f32x2 bk = nbk;
;             SC_LOAD(t + 1)
;             __builtin_amdgcn_sched_barrier(0);
;             f32x2 aA = sp[0] * c[0].xy, aY = sp[0] * c[2].xy;
;             aA = sp[1] * c[0].zw + aA; aY = sp[1] * c[2].zw + aY;
;             aA = sp[2] * c[1].xy + aA; aY = sp[2] * c[3].xy + aY;
;             aA = sp[3] * c[1].zw + aA; aY = sp[3] * c[3].zw + aY;
;             float da = aA.x + aA.y, dy = aY.x + aY.y;
;             asm("s_nop 1\n\t"
;                 "v_add_f32_dpp %0, %0, %0 quad_perm:[1,0,3,2] row_mask:0xf bank_mask:0xf bound_ctrl:1\n\t"
;                 "v_add_f32_dpp %1, %1, %1 quad_perm:[1,0,3,2] row_mask:0xf bank_mask:0xf bound_ctrl:1\n\t"
;                 "s_nop 0\n\t"
;                 "v_add_f32_dpp %0, %0, %0 quad_perm:[2,3,0,1] row_mask:0xf bank_mask:0xf bound_ctrl:1\n\t"
;                 "v_add_f32_dpp %1, %1, %1 quad_perm:[2,3,0,1] row_mask:0xf bank_mask:0xf bound_ctrl:1\n\t"
;                 "s_nop 0\n\t"
;                 "v_add_f32_dpp %0, %0, %0 row_half_mirror row_mask:0xf bank_mask:0xf bound_ctrl:1\n\t"
;                 "v_add_f32_dpp %1, %1, %1 row_half_mirror row_mask:0xf bank_mask:0xf bound_ctrl:1"
;                 : "+v"(da), "+v"(dy));
;             {
;                 f32x2 t0;
;                 t0 = c[8].xy * v0; t0 = c[6].xy * da + t0; sp[0] = sp[0] * c[4].xy + t0;
;                 t0 = c[8].zw * v0; t0 = c[6].zw * da + t0; sp[1] = sp[1] * c[4].zw + t0;
;                 t0 = c[9].xy * v0; t0 = c[7].xy * da + t0; sp[2] = sp[2] * c[5].xy + t0;
;                 t0 = c[9].zw * v0; t0 = c[7].zw * da + t0; sp[3] = sp[3] * c[5].zw + t0;
;             }
;             ybb[t * 32] = dy + da * bk.x + v0 * bk.y;
	v_pk_mul_f32 v[122:123], v[38:39], v[42:43]
	v_pk_mul_f32 v[124:125], v[38:39], v[50:51]
	v_pk_fma_f32 v[122:123], v[36:37], v[40:41], v[122:123]
	v_pk_fma_f32 v[124:125], v[36:37], v[48:49], v[124:125]
	v_pk_fma_f32 v[122:123], v[32:33], v[44:45], v[122:123]
	v_pk_fma_f32 v[124:125], v[32:33], v[52:53], v[124:125]
	v_pk_fma_f32 v[122:123], v[34:35], v[46:47], v[122:123]
	v_pk_fma_f32 v[124:125], v[34:35], v[54:55], v[124:125]
	v_pk_mul_f32 v[126:127], v[72:73], v[94:95] op_sel_hi:[1,0]
	v_add_f32_e32 v166, v122, v123
	v_add_f32_e32 v168, v124, v125
	v_pk_mul_f32 v[128:129], v[74:75], v[94:95] op_sel_hi:[1,0]
	v_pk_mul_f32 v[130:131], v[76:77], v[94:95] op_sel_hi:[1,0]
	v_add_f32_dpp v166, v166, v166 quad_perm:[1,0,3,2] row_mask:0xf bank_mask:0xf bound_ctrl:1
	v_add_f32_dpp v168, v168, v168 quad_perm:[1,0,3,2] row_mask:0xf bank_mask:0xf bound_ctrl:1
	v_pk_mul_f32 v[132:133], v[78:79], v[94:95] op_sel_hi:[1,0]
	v_pk_fma_f32 v[126:127], v[36:37], v[56:57], v[126:127]
	v_add_f32_dpp v166, v166, v166 quad_perm:[2,3,0,1] row_mask:0xf bank_mask:0xf bound_ctrl:1
	v_add_f32_dpp v168, v168, v168 quad_perm:[2,3,0,1] row_mask:0xf bank_mask:0xf bound_ctrl:1
	v_pk_fma_f32 v[128:129], v[38:39], v[58:59], v[128:129]
	v_pk_fma_f32 v[130:131], v[32:33], v[60:61], v[130:131]
	v_add_f32_dpp v166, v166, v166 row_half_mirror row_mask:0xf bank_mask:0xf bound_ctrl:1
	v_add_f32_dpp v168, v168, v168 row_half_mirror row_mask:0xf bank_mask:0xf bound_ctrl:1
	v_pk_fma_f32 v[132:133], v[34:35], v[62:63], v[132:133]
	v_mov_b32_e32 v167, v94
	v_pk_mul_f32 v[134:135], v[166:167], v[108:109]
	v_pk_fma_f32 v[36:37], v[64:65], v[166:167], v[126:127] op_sel_hi:[1,0,1]
	v_pk_fma_f32 v[38:39], v[66:67], v[166:167], v[128:129] op_sel_hi:[1,0,1]
	v_pk_fma_f32 v[32:33], v[68:69], v[166:167], v[130:131] op_sel_hi:[1,0,1]
	v_pk_fma_f32 v[34:35], v[70:71], v[166:167], v[132:133] op_sel_hi:[1,0,1]
	v_add_f32_e32 v136, v168, v134
	v_add_f32_e32 v136, v135, v136
	ds_write_b32 v95, v136 offset:1536
	ds_read_b128 v[40:43], v120 offset:17920
	ds_read_b128 v[44:47], v120 offset:17936
	ds_read_b128 v[48:51], v120 offset:18176
	ds_read_b128 v[52:55], v120 offset:18192
	ds_read_b128 v[56:59], v120 offset:18432
	ds_read_b128 v[60:63], v120 offset:18448
	ds_read_b128 v[64:67], v120 offset:18688
	ds_read_b128 v[68:71], v120 offset:18704
	ds_read_b128 v[72:75], v120 offset:18944
	ds_read_b128 v[76:79], v120 offset:18960
	ds_read_b32 v94, v96 offset:24064
	ds_read_b64 v[108:109], v121 offset:24800
	s_waitcnt lgkmcnt(12)
	v_pk_mul_f32 v[122:123], v[38:39], v[192:193]
	v_pk_mul_f32 v[124:125], v[38:39], v[200:201]
	v_pk_fma_f32 v[122:123], v[36:37], v[190:191], v[122:123]
	v_pk_fma_f32 v[124:125], v[36:37], v[198:199], v[124:125]
	v_pk_fma_f32 v[122:123], v[32:33], v[194:195], v[122:123]
	v_pk_fma_f32 v[124:125], v[32:33], v[202:203], v[124:125]
	v_pk_fma_f32 v[122:123], v[34:35], v[196:197], v[122:123]
	v_pk_fma_f32 v[124:125], v[34:35], v[204:205], v[124:125]
	v_pk_mul_f32 v[126:127], v[222:223], v[230:231] op_sel_hi:[1,0]
	v_add_f32_e32 v166, v122, v123
	v_add_f32_e32 v168, v124, v125
	v_pk_mul_f32 v[128:129], v[224:225], v[230:231] op_sel_hi:[1,0]
	v_pk_mul_f32 v[130:131], v[226:227], v[230:231] op_sel_hi:[1,0]
	v_add_f32_dpp v166, v166, v166 quad_perm:[1,0,3,2] row_mask:0xf bank_mask:0xf bound_ctrl:1
	v_add_f32_dpp v168, v168, v168 quad_perm:[1,0,3,2] row_mask:0xf bank_mask:0xf bound_ctrl:1
	v_pk_mul_f32 v[132:133], v[228:229], v[230:231] op_sel_hi:[1,0]
	v_pk_fma_f32 v[126:127], v[36:37], v[206:207], v[126:127]
	v_add_f32_dpp v166, v166, v166 quad_perm:[2,3,0,1] row_mask:0xf bank_mask:0xf bound_ctrl:1
	v_add_f32_dpp v168, v168, v168 quad_perm:[2,3,0,1] row_mask:0xf bank_mask:0xf bound_ctrl:1
	v_pk_fma_f32 v[128:129], v[38:39], v[208:209], v[128:129]
	v_pk_fma_f32 v[130:131], v[32:33], v[210:211], v[130:131]
	v_add_f32_dpp v166, v166, v166 row_half_mirror row_mask:0xf bank_mask:0xf bound_ctrl:1
	v_add_f32_dpp v168, v168, v168 row_half_mirror row_mask:0xf bank_mask:0xf bound_ctrl:1
	v_pk_fma_f32 v[132:133], v[34:35], v[212:213], v[132:133]
	v_mov_b32_e32 v167, v230
	v_pk_mul_f32 v[134:135], v[166:167], v[232:233]
	v_pk_fma_f32 v[36:37], v[214:215], v[166:167], v[126:127] op_sel_hi:[1,0,1]
	v_pk_fma_f32 v[38:39], v[216:217], v[166:167], v[128:129] op_sel_hi:[1,0,1]
	v_pk_fma_f32 v[32:33], v[218:219], v[166:167], v[130:131] op_sel_hi:[1,0,1]
	v_pk_fma_f32 v[34:35], v[220:221], v[166:167], v[132:133] op_sel_hi:[1,0,1]
	v_add_f32_e32 v136, v168, v134
	v_add_f32_e32 v136, v135, v136
	ds_write_b32 v95, v136 offset:1664
	ds_read_b128 v[190:193], v120 offset:19200
	ds_read_b128 v[194:197], v120 offset:19216
	ds_read_b128 v[198:201], v120 offset:19456
	ds_read_b128 v[202:205], v120 offset:19472
	ds_read_b128 v[206:209], v120 offset:19712
	ds_read_b128 v[210:213], v120 offset:19728
	ds_read_b128 v[214:217], v120 offset:19968
	ds_read_b128 v[218:221], v120 offset:19984
	ds_read_b128 v[222:225], v120 offset:20224
	ds_read_b128 v[226:229], v120 offset:20240
	ds_read_b32 v230, v96 offset:24320
	ds_read_b64 v[232:233], v121 offset:24816
	s_waitcnt lgkmcnt(12)
; DI void scan_item(const __attribute__((address_space(4))) Args& a, LAS unsigned char* lds, int ws_, bool is_prompt, int seq, int h, int half, bool dry = false) {
;     ...
; #pragma unroll 4
;         for (int t = 0; t < SC_CH; ++t) {
;             f32x4 c[10];
; #pragma unroll
;             for (int q = 0; q < 10; ++q) c[q] = n[q];
;             const float v0 = nv; const f32x2 bk = nbk;
;             SC_LOAD(t + 1)
;             __builtin_amdgcn_sched_barrier(0);
;             f32x2 aA = sp[0] * c[0].xy, aY = sp[0] * c[2].xy;
;             aA = sp[1] * c[0].zw + aA; aY = sp[1] * c[2].zw + aY;
;             aA = sp[2] * c[1].xy + aA; aY = sp[2] * c[3].xy + aY;
;             aA = sp[3] * c[1].zw + aA; aY = sp[3] * c[3].zw + aY;
;             float da = aA.x + aA.y, dy = aY.x + aY.y;
;             asm("s_nop 1\n\t"
;                 "v_add_f32_dpp %0, %0, %0 quad_perm:[1,0,3,2] row_mask:0xf bank_mask:0xf bound_ctrl:1\n\t"
;                 "v_add_f32_dpp %1, %1, %1 quad_perm:[1,0,3,2] row_mask:0xf bank_mask:0xf bound_ctrl:1\n\t"
;                 "s_nop 0\n\t"
;                 "v_add_f32_dpp %0, %0, %0 quad_perm:[2,3,0,1] row_mask:0xf bank_mask:0xf bound_ctrl:1\n\t"
;                 "v_add_f32_dpp %1, %1, %1 quad_perm:[2,3,0,1] row_mask:0xf bank_mask:0xf bound_ctrl:1\n\t"
;                 "s_nop 0\n\t"
;                 "v_add_f32_dpp %0, %0, %0 row_half_mirror row_mask:0xf bank_mask:0xf bound_ctrl:1\n\t"
;                 "v_add_f32_dpp %1, %1, %1 row_half_mirror row_mask:0xf bank_mask:0xf bound_ctrl:1"
;                 : "+v"(da), "+v"(dy));
;             {
;                 f32x2 t0;
;                 t0 = c[8].xy * v0; t0 = c[6].xy * da + t0; sp[0] = sp[0] * c[4].xy + t0;
;                 t0 = c[8].zw * v0; t0 = c[6].zw * da + t0; sp[1] = sp[1] * c[4].zw + t0;
;                 t0 = c[9].xy * v0; t0 = c[7].xy * da + t0; sp[2] = sp[2] * c[5].xy + t0;
;                 t0 = c[9].zw * v0; t0 = c[7].zw * da + t0; sp[3] = sp[3] * c[5].zw + t0;
;             }
;             ybb[t * 32] = dy + da * bk.x + v0 * bk.y;
;         }
;     ...
;     };
;     if (!consumer) { load_raw(0); produce(0, 0); if (NCH > 1) load_raw(1); }
;     __syncthreads();
;     for (int ch = 0; ch < NCH; ++ch) {
;         if (consumer) consume(ch & 1);
	v_pk_mul_f32 v[122:123], v[38:39], v[42:43]
	v_pk_mul_f32 v[124:125], v[38:39], v[50:51]
	v_pk_fma_f32 v[122:123], v[36:37], v[40:41], v[122:123]
	v_pk_fma_f32 v[124:125], v[36:37], v[48:49], v[124:125]
	v_pk_fma_f32 v[122:123], v[32:33], v[44:45], v[122:123]
	v_pk_fma_f32 v[124:125], v[32:33], v[52:53], v[124:125]
	v_pk_fma_f32 v[122:123], v[34:35], v[46:47], v[122:123]
	v_pk_fma_f32 v[124:125], v[34:35], v[54:55], v[124:125]
	v_pk_mul_f32 v[126:127], v[72:73], v[94:95] op_sel_hi:[1,0]
	v_add_f32_e32 v166, v122, v123
	v_add_f32_e32 v168, v124, v125
	v_pk_mul_f32 v[128:129], v[74:75], v[94:95] op_sel_hi:[1,0]
	v_pk_mul_f32 v[130:131], v[76:77], v[94:95] op_sel_hi:[1,0]
	v_add_f32_dpp v166, v166, v166 quad_perm:[1,0,3,2] row_mask:0xf bank_mask:0xf bound_ctrl:1
	v_add_f32_dpp v168, v168, v168 quad_perm:[1,0,3,2] row_mask:0xf bank_mask:0xf bound_ctrl:1
	v_pk_mul_f32 v[132:133], v[78:79], v[94:95] op_sel_hi:[1,0]
	v_pk_fma_f32 v[126:127], v[36:37], v[56:57], v[126:127]
	v_add_f32_dpp v166, v166, v166 quad_perm:[2,3,0,1] row_mask:0xf bank_mask:0xf bound_ctrl:1
	v_add_f32_dpp v168, v168, v168 quad_perm:[2,3,0,1] row_mask:0xf bank_mask:0xf bound_ctrl:1
	v_pk_fma_f32 v[128:129], v[38:39], v[58:59], v[128:129]
	v_pk_fma_f32 v[130:131], v[32:33], v[60:61], v[130:131]
	v_add_f32_dpp v166, v166, v166 row_half_mirror row_mask:0xf bank_mask:0xf bound_ctrl:1
	v_add_f32_dpp v168, v168, v168 row_half_mirror row_mask:0xf bank_mask:0xf bound_ctrl:1
	v_pk_fma_f32 v[132:133], v[34:35], v[62:63], v[132:133]
	v_mov_b32_e32 v167, v94
	v_pk_mul_f32 v[134:135], v[166:167], v[108:109]
	v_pk_fma_f32 v[36:37], v[64:65], v[166:167], v[126:127] op_sel_hi:[1,0,1]
	v_pk_fma_f32 v[38:39], v[66:67], v[166:167], v[128:129] op_sel_hi:[1,0,1]
	v_pk_fma_f32 v[32:33], v[68:69], v[166:167], v[130:131] op_sel_hi:[1,0,1]
	v_pk_fma_f32 v[34:35], v[70:71], v[166:167], v[132:133] op_sel_hi:[1,0,1]
	v_add_f32_e32 v136, v168, v134
	v_add_f32_e32 v136, v135, v136
	ds_write_b32 v95, v136 offset:1792
	s_waitcnt lgkmcnt(0)
	v_pk_mul_f32 v[122:123], v[38:39], v[192:193]
	v_pk_mul_f32 v[124:125], v[38:39], v[200:201]
	v_pk_fma_f32 v[122:123], v[36:37], v[190:191], v[122:123]
	v_pk_fma_f32 v[124:125], v[36:37], v[198:199], v[124:125]
	v_pk_fma_f32 v[122:123], v[32:33], v[194:195], v[122:123]
	v_pk_fma_f32 v[124:125], v[32:33], v[202:203], v[124:125]
	v_pk_fma_f32 v[122:123], v[34:35], v[196:197], v[122:123]
	v_pk_fma_f32 v[124:125], v[34:35], v[204:205], v[124:125]
	v_pk_mul_f32 v[126:127], v[222:223], v[230:231] op_sel_hi:[1,0]
	v_add_f32_e32 v166, v122, v123
	v_add_f32_e32 v168, v124, v125
	v_pk_mul_f32 v[128:129], v[224:225], v[230:231] op_sel_hi:[1,0]
	v_pk_mul_f32 v[130:131], v[226:227], v[230:231] op_sel_hi:[1,0]
	v_add_f32_dpp v166, v166, v166 quad_perm:[1,0,3,2] row_mask:0xf bank_mask:0xf bound_ctrl:1
	v_add_f32_dpp v168, v168, v168 quad_perm:[1,0,3,2] row_mask:0xf bank_mask:0xf bound_ctrl:1
	v_pk_mul_f32 v[132:133], v[228:229], v[230:231] op_sel_hi:[1,0]
	v_pk_fma_f32 v[126:127], v[36:37], v[206:207], v[126:127]
	v_add_f32_dpp v166, v166, v166 quad_perm:[2,3,0,1] row_mask:0xf bank_mask:0xf bound_ctrl:1
	v_add_f32_dpp v168, v168, v168 quad_perm:[2,3,0,1] row_mask:0xf bank_mask:0xf bound_ctrl:1
	v_pk_fma_f32 v[128:129], v[38:39], v[208:209], v[128:129]
	v_pk_fma_f32 v[130:131], v[32:33], v[210:211], v[130:131]
	v_add_f32_dpp v166, v166, v166 row_half_mirror row_mask:0xf bank_mask:0xf bound_ctrl:1
	v_add_f32_dpp v168, v168, v168 row_half_mirror row_mask:0xf bank_mask:0xf bound_ctrl:1
	v_pk_fma_f32 v[132:133], v[34:35], v[212:213], v[132:133]
	v_mov_b32_e32 v167, v230
	v_pk_mul_f32 v[134:135], v[166:167], v[232:233]
	v_pk_fma_f32 v[36:37], v[214:215], v[166:167], v[126:127] op_sel_hi:[1,0,1]
	v_pk_fma_f32 v[38:39], v[216:217], v[166:167], v[128:129] op_sel_hi:[1,0,1]
	v_pk_fma_f32 v[32:33], v[218:219], v[166:167], v[130:131] op_sel_hi:[1,0,1]
	v_pk_fma_f32 v[34:35], v[220:221], v[166:167], v[132:133] op_sel_hi:[1,0,1]
	v_add_f32_e32 v136, v168, v134
	v_add_f32_e32 v136, v135, v136
	ds_write_b32 v95, v136 offset:1920
	s_setprio 0
	s_add_i32 s24, s24, 1
	s_branch .LBB0_1524
